# s=5 phase: blocks 256..511 run norm1 before combine (CU partners run combine first), overlapping the two kinds of work per CU
# speedup vs baseline: 1.0089x; 1.0005x over previous
_Z9mk_kernel6Paramsii:
	s_mov_b32 s100, 0
	s_mov_b32 s101, 0
	s_load_dwordx8 s[52:59], s[0:1], 0x100
	s_load_dwordx2 s[96:97], s[0:1], 0x120
	s_add_u32 s4, s0, 0x120
	s_addc_u32 s5, s1, 0
	v_writelane_b32 v250, s2, 0
	s_waitcnt lgkmcnt(0)
	s_cmpk_gt_i32 s59, 0x3e8
	s_cbranch_scc1 .LBB0_2
	v_and_b32_e32 v168, 0x3ff, v0
	s_load_dword s24, s[0:1], 0x128
	s_cbranch_execz .LBB0_3
	s_branch .LBB0_14

.LBB0_173:
	v_readlane_b32 s1, v254, 56
	s_andn2_b64 vcc, exec, s[36:37]
	s_mov_b32 s36, s1
	v_readlane_b32 s1, v254, 57
	s_mov_b32 s44, s1
	s_cbranch_vccnz .LBB0_183
	v_readlane_b32 s2, v250, 0
	s_mov_b32 s101, 0
	s_nop 0
	s_cmpk_lt_u32 s2, 0x100
	s_cbranch_scc1 .Lmy_s5_cmb
	s_mov_b32 s101, 1
	s_movk_i32 s1, 0x3000
	s_mov_b64 s[36:37], exec
	s_waitcnt vmcnt(0) lgkmcnt(0)
	s_branch .LBB0_177
.Lmy_s5_cmb:
	s_waitcnt vmcnt(0) lgkmcnt(0)
	v_mov_b32_e32 v6, v168
	v_mov_b32_e32 v0, v168
	v_readlane_b32 s0, v254, 7
	v_ashrrev_i32_e32 v0, 6, v0
	s_nop 0
	v_add_u32_e32 v0, s0, v0
	v_readlane_b32 s0, v254, 46
	v_readlane_b32 s1, v254, 47
	s_movk_i32 s1, 0x3000
	s_nop 0
	v_cmp_gt_i32_e32 vcc, s1, v0
	s_and_saveexec_b64 s[36:37], vcc
	s_cbranch_execz .LBB0_177
	v_cmp_lt_i32_e32 vcc, v185, v182
	v_lshlrev_b32_e32 v1, 3, v6
	v_readlane_b32 s2, v254, 63
	v_cndmask_b32_e32 v3, v179, v185, vcc
	v_cmp_lt_i32_e32 vcc, v186, v182
	v_readlane_b32 s40, v250, 33
	v_readlane_b32 s41, v250, 34
	v_cndmask_b32_e32 v4, v179, v186, vcc
	v_cmp_lt_i32_e32 vcc, v187, v182
	v_lshlrev_b32_e32 v8, 2, v4
	v_lshlrev_b32_e32 v3, 2, v3
	v_cndmask_b32_e32 v4, v179, v187, vcc
	v_lshlrev_b32_e32 v9, 2, v4
	v_and_or_b32 v4, v1, 56, s2
	v_ashrrev_i32_e32 v1, 31, v0
	v_lshlrev_b64 v[10:11], 10, v[0:1]
	v_and_b32_e32 v1, 63, v6
	v_readlane_b32 s2, v254, 13
	v_ashrrev_i32_e32 v5, 31, v4
	v_lshl_or_b32 v10, v1, 4, v10
	v_readlane_b32 s3, v254, 14
	v_lshl_add_u64 v[4:5], v[4:5], 2, s[40:41]
	s_mov_b64 s[38:39], 0
	v_lshl_add_u64 v[6:7], s[2:3], 0, v[10:11]
	v_readlane_b32 s42, v250, 35
	v_readlane_b32 s43, v250, 36
	v_readlane_b32 s44, v250, 37
	v_readlane_b32 s45, v250, 38
	v_readlane_b32 s46, v250, 39
	v_readlane_b32 s47, v250, 40
	v_readlane_b32 s48, v250, 41
	v_readlane_b32 s49, v250, 42
	v_readlane_b32 s50, v250, 43
	v_readlane_b32 s51, v250, 44
	v_readlane_b32 s52, v250, 45
	v_readlane_b32 s53, v250, 46
	v_readlane_b32 s54, v250, 47
	v_readlane_b32 s55, v250, 48

.LBB0_177:
	s_cmp_eq_u32 s101, 2
	s_cbranch_scc0 .Lmy_s5_n1
	s_or_b64 exec, exec, s[36:37]
	s_mov_b32 s101, 0
	v_readlane_b32 s1, v254, 56
	s_nop 0
	s_mov_b32 s36, s1
	v_readlane_b32 s1, v254, 57
	s_nop 0
	s_mov_b32 s44, s1
	s_branch .LBB0_183

.LBB0_182:
	s_or_b64 exec, exec, s[38:39]
	s_cmp_eq_u32 s101, 1
	s_cbranch_scc0 .Lmy_s5_e
	s_mov_b32 s101, 2
	s_branch .Lmy_s5_cmb
.Lmy_s5_e:
	v_readlane_b32 s1, v254, 56
	s_mov_b32 s36, s1
	v_readlane_b32 s1, v254, 57
	s_mov_b32 s44, s1
.LBB0_183:
	s_mov_b64 s[40:41], 0
